# out-proj epilogue: per-block row mean/rstd loads issued one block ahead (no store drain), on top of the rope permlane version
# baseline (speedup 1.0000x reference)
.LBB0_643:
	s_and_b64 vcc, exec, s[38:39]
	s_cbranch_vccnz .Lst_1
	v_or_b32_e32 v226, 16, v186
	v_ashrrev_i32_e32 v227, 31, v226
	v_lshl_add_u64 v[226:227], v[226:227], 3, s[6:7]
	global_load_dwordx2 v[228:229], v[226:227], off
.Lst_1:
	v_ashrrev_i32_e32 v189, 31, v188
	v_lshlrev_b64 v[218:219], 10, v[188:189]
	v_lshl_add_u64 v[218:219], v[218:219], 0, v[184:185]
	s_and_b64 s[10:11], s[10:11], exec
	s_cselect_b32 s63, s83, s88
	s_cselect_b32 s62, s68, s89
	v_lshlrev_b64 v[222:223], 2, v[218:219]
	v_lshl_add_u64 v[224:225], s[62:63], 0, v[222:223]
	global_load_dwordx4 v[234:237], v[224:225], off
	global_load_dwordx4 v[238:241], v[224:225], off offset:64
	global_load_dwordx4 v[242:245], v[224:225], off offset:512
	global_load_dwordx4 v[246:249], v[224:225], off offset:576
	s_waitcnt vmcnt(3)
	v_pk_add_f32 v[132:133], v[132:133], 1.0 op_sel_hi:[1,0]
	v_pk_add_f32 v[130:131], v[130:131], 1.0 op_sel_hi:[1,0]
	s_cselect_b32 s11, s73, s79
	s_cselect_b32 s10, s33, s78
	v_lshl_add_u64 v[222:223], s[10:11], 0, v[222:223]
	s_and_b64 vcc, exec, s[38:39]
	v_sub_f32_e32 v235, v235, v208
	v_sub_f32_e32 v234, v234, v208
	v_sub_f32_e32 v237, v237, v208
	v_sub_f32_e32 v236, v236, v208
	v_pk_mul_f32 v[236:237], v[194:195], v[236:237] op_sel_hi:[0,1]
	v_pk_mul_f32 v[234:235], v[194:195], v[234:235] op_sel_hi:[0,1]
	v_pk_fma_f32 v[234:235], v[158:159], v[234:235], v[162:163]
	v_pk_fma_f32 v[236:237], v[156:157], v[236:237], v[160:161]
	v_pk_fma_f32 v[126:127], v[126:127], v[130:131], v[234:235]
	v_pk_fma_f32 v[128:129], v[128:129], v[132:133], v[236:237]
	global_store_dwordx4 v[222:223], v[126:129], off
	s_nop 0
	s_nop 0
	v_pk_add_f32 v[126:127], v[136:137], 1.0 op_sel_hi:[1,0]
	v_pk_add_f32 v[128:129], v[134:135], 1.0 op_sel_hi:[1,0]
	s_waitcnt vmcnt(3)
	v_sub_f32_e32 v135, v239, v208
	v_sub_f32_e32 v134, v238, v208
	v_sub_f32_e32 v137, v241, v208
	v_sub_f32_e32 v136, v240, v208
	v_pk_mul_f32 v[136:137], v[194:195], v[136:137] op_sel_hi:[0,1]
	v_pk_mul_f32 v[134:135], v[194:195], v[134:135] op_sel_hi:[0,1]
	v_pk_fma_f32 v[134:135], v[152:153], v[134:135], v[154:155]
	v_pk_fma_f32 v[136:137], v[164:165], v[136:137], v[170:171]
	v_pk_fma_f32 v[122:123], v[122:123], v[128:129], v[134:135]
	v_pk_fma_f32 v[124:125], v[124:125], v[126:127], v[136:137]
	global_store_dwordx4 v[222:223], v[122:125], off offset:64
	s_nop 0
	s_waitcnt vmcnt(3)
	v_sub_f32_e32 v243, v243, v208
	v_sub_f32_e32 v242, v242, v208
	v_sub_f32_e32 v245, v245, v208
	v_sub_f32_e32 v244, v244, v208
	v_pk_mul_f32 v[244:245], v[194:195], v[244:245] op_sel_hi:[0,1]
	v_pk_mul_f32 v[242:243], v[194:195], v[242:243] op_sel_hi:[0,1]
	v_pk_add_f32 v[122:123], v[140:141], 1.0 op_sel_hi:[1,0]
	v_pk_add_f32 v[124:125], v[138:139], 1.0 op_sel_hi:[1,0]
	v_pk_fma_f32 v[242:243], v[174:175], v[242:243], v[178:179]
	v_pk_fma_f32 v[244:245], v[172:173], v[244:245], v[176:177]
	v_pk_fma_f32 v[118:119], v[118:119], v[124:125], v[242:243]
	v_pk_fma_f32 v[120:121], v[120:121], v[122:123], v[244:245]
	global_store_dwordx4 v[222:223], v[118:121], off offset:512
	s_nop 0
	s_waitcnt vmcnt(3)
	v_sub_f32_e32 v247, v247, v208
	v_sub_f32_e32 v246, v246, v208
	v_sub_f32_e32 v249, v249, v208
	v_sub_f32_e32 v248, v248, v208
	v_pk_mul_f32 v[248:249], v[194:195], v[248:249] op_sel_hi:[0,1]
	v_pk_mul_f32 v[246:247], v[194:195], v[246:247] op_sel_hi:[0,1]
	v_pk_add_f32 v[118:119], v[144:145], 1.0 op_sel_hi:[1,0]
	v_pk_add_f32 v[120:121], v[142:143], 1.0 op_sel_hi:[1,0]
	v_pk_fma_f32 v[246:247], v[166:167], v[246:247], v[168:169]
	v_pk_fma_f32 v[248:249], v[180:181], v[248:249], v[182:183]
	v_pk_fma_f32 v[114:115], v[114:115], v[120:121], v[246:247]
	v_pk_fma_f32 v[116:117], v[116:117], v[118:119], v[248:249]
	global_store_dwordx4 v[222:223], v[114:117], off offset:576
	s_cbranch_vccnz .LBB0_645
	s_nop 0
	v_mov_b32_e32 v190, v228
	v_mov_b32_e32 v191, v229
	v_mov_b32_e32 v192, v191
.LBB0_645:
	s_and_b64 vcc, exec, s[38:39]
	s_cbranch_vccnz .Lst_2
	v_or_b32_e32 v226, 32, v186
	v_ashrrev_i32_e32 v227, 31, v226
	v_lshl_add_u64 v[226:227], v[226:227], 3, s[6:7]
	global_load_dwordx2 v[228:229], v[226:227], off
.Lst_2:
	s_nop 0
	v_or_b32_e32 v114, 16, v188
	v_ashrrev_i32_e32 v115, 31, v114
	v_lshlrev_b64 v[114:115], 10, v[114:115]
	v_lshl_add_u64 v[114:115], v[114:115], 0, v[184:185]
	v_lshlrev_b64 v[134:135], 2, v[114:115]
	v_lshl_add_u64 v[136:137], s[62:63], 0, v[134:135]
	global_load_dwordx4 v[234:237], v[136:137], off
	global_load_dwordx4 v[238:241], v[136:137], off offset:64
	global_load_dwordx4 v[242:245], v[136:137], off offset:512
	global_load_dwordx4 v[246:249], v[136:137], off offset:576
	v_lshl_add_u64 v[134:135], s[10:11], 0, v[134:135]
	s_and_b64 vcc, exec, s[38:39]
	s_waitcnt vmcnt(3)
	v_sub_f32_e32 v235, v235, v190
	v_sub_f32_e32 v234, v234, v190
	v_sub_f32_e32 v237, v237, v190
	v_sub_f32_e32 v236, v236, v190
	v_pk_mul_f32 v[236:237], v[192:193], v[236:237] op_sel_hi:[0,1]
	v_pk_mul_f32 v[234:235], v[192:193], v[234:235] op_sel_hi:[0,1]
	v_pk_fma_f32 v[234:235], v[158:159], v[234:235], v[162:163]
	v_pk_fma_f32 v[236:237], v[156:157], v[236:237], v[160:161]
	v_pk_fma_f32 v[110:111], v[110:111], v[130:131], v[234:235]
	v_pk_fma_f32 v[112:113], v[112:113], v[132:133], v[236:237]
	global_store_dwordx4 v[134:135], v[110:113], off
	s_nop 0
	s_waitcnt vmcnt(3)
	v_sub_f32_e32 v239, v239, v190
	v_sub_f32_e32 v238, v238, v190
	v_sub_f32_e32 v241, v241, v190
	v_sub_f32_e32 v240, v240, v190
	v_pk_mul_f32 v[240:241], v[192:193], v[240:241] op_sel_hi:[0,1]
	v_pk_mul_f32 v[238:239], v[192:193], v[238:239] op_sel_hi:[0,1]
	v_pk_fma_f32 v[238:239], v[152:153], v[238:239], v[154:155]
	v_pk_fma_f32 v[240:241], v[164:165], v[240:241], v[170:171]
	v_pk_fma_f32 v[106:107], v[106:107], v[128:129], v[238:239]
	v_pk_fma_f32 v[108:109], v[108:109], v[126:127], v[240:241]
	global_store_dwordx4 v[134:135], v[106:109], off offset:64
	s_nop 0
	s_waitcnt vmcnt(3)
	v_sub_f32_e32 v243, v243, v190
	v_sub_f32_e32 v242, v242, v190
	v_sub_f32_e32 v245, v245, v190
	v_sub_f32_e32 v244, v244, v190
	v_pk_mul_f32 v[244:245], v[192:193], v[244:245] op_sel_hi:[0,1]
	v_pk_mul_f32 v[242:243], v[192:193], v[242:243] op_sel_hi:[0,1]
	v_pk_fma_f32 v[242:243], v[174:175], v[242:243], v[178:179]
	v_pk_fma_f32 v[244:245], v[172:173], v[244:245], v[176:177]
	v_pk_fma_f32 v[102:103], v[102:103], v[124:125], v[242:243]
	v_pk_fma_f32 v[104:105], v[104:105], v[122:123], v[244:245]
	global_store_dwordx4 v[134:135], v[102:105], off offset:512
	s_nop 0
	s_waitcnt vmcnt(3)
	v_sub_f32_e32 v249, v249, v190
	v_sub_f32_e32 v247, v247, v190
	v_sub_f32_e32 v246, v246, v190
	v_sub_f32_e32 v248, v248, v190
	v_pk_mul_f32 v[248:249], v[192:193], v[248:249] op_sel_hi:[0,1]
	v_pk_mul_f32 v[246:247], v[192:193], v[246:247] op_sel_hi:[0,1]
	v_pk_fma_f32 v[246:247], v[166:167], v[246:247], v[168:169]
	v_pk_fma_f32 v[248:249], v[180:181], v[248:249], v[182:183]
	v_pk_fma_f32 v[98:99], v[98:99], v[120:121], v[246:247]
	v_pk_fma_f32 v[100:101], v[100:101], v[118:119], v[248:249]
	global_store_dwordx4 v[134:135], v[98:101], off offset:576
	v_mov_b32_e32 v102, 1.0
	v_mov_b32_e32 v104, 0
	v_mov_b32_e32 v98, 0
	v_mov_b32_e32 v100, 1.0
	s_cbranch_vccnz .LBB0_647
	v_mov_b32_e32 v104, v228
	v_mov_b32_e32 v105, v229
	v_mov_b32_e32 v100, v105
.LBB0_647:
	s_and_b64 vcc, exec, s[38:39]
	s_cbranch_vccnz .Lst_3
	v_or_b32_e32 v226, 48, v186
	v_ashrrev_i32_e32 v227, 31, v226
	v_lshl_add_u64 v[226:227], v[226:227], 3, s[6:7]
	global_load_dwordx2 v[228:229], v[226:227], off
.Lst_3:
	v_or_b32_e32 v106, 32, v188
	v_ashrrev_i32_e32 v107, 31, v106
	v_lshlrev_b64 v[106:107], 10, v[106:107]
	v_lshl_add_u64 v[106:107], v[106:107], 0, v[184:185]
	v_lshlrev_b64 v[110:111], 2, v[106:107]
	v_lshl_add_u64 v[112:113], s[62:63], 0, v[110:111]
	global_load_dwordx4 v[234:237], v[112:113], off
	global_load_dwordx4 v[238:241], v[112:113], off offset:64
	global_load_dwordx4 v[242:245], v[112:113], off offset:512
	global_load_dwordx4 v[246:249], v[112:113], off offset:576
	v_lshl_add_u64 v[110:111], s[10:11], 0, v[110:111]
	s_and_b64 vcc, exec, s[38:39]
	s_waitcnt vmcnt(3)
	v_sub_f32_e32 v235, v235, v104
	v_sub_f32_e32 v234, v234, v104
	v_sub_f32_e32 v237, v237, v104
	v_sub_f32_e32 v236, v236, v104
	v_pk_mul_f32 v[236:237], v[100:101], v[236:237] op_sel_hi:[0,1]
	v_pk_mul_f32 v[234:235], v[100:101], v[234:235] op_sel_hi:[0,1]
	v_pk_fma_f32 v[234:235], v[158:159], v[234:235], v[162:163]
	v_pk_fma_f32 v[236:237], v[156:157], v[236:237], v[160:161]
	v_pk_fma_f32 v[94:95], v[94:95], v[130:131], v[234:235]
	v_pk_fma_f32 v[96:97], v[96:97], v[132:133], v[236:237]
	global_store_dwordx4 v[110:111], v[94:97], off
	s_nop 0
	s_waitcnt vmcnt(3)
	v_sub_f32_e32 v239, v239, v104
	v_sub_f32_e32 v238, v238, v104
	v_sub_f32_e32 v241, v241, v104
	v_sub_f32_e32 v240, v240, v104
	v_pk_mul_f32 v[240:241], v[100:101], v[240:241] op_sel_hi:[0,1]
	v_pk_mul_f32 v[238:239], v[100:101], v[238:239] op_sel_hi:[0,1]
	v_pk_fma_f32 v[238:239], v[152:153], v[238:239], v[154:155]
	v_pk_fma_f32 v[240:241], v[164:165], v[240:241], v[170:171]
	v_pk_fma_f32 v[90:91], v[90:91], v[128:129], v[238:239]
	v_pk_fma_f32 v[92:93], v[92:93], v[126:127], v[240:241]
	global_store_dwordx4 v[110:111], v[90:93], off offset:64
	s_nop 0
	s_waitcnt vmcnt(3)
	v_sub_f32_e32 v243, v243, v104
	v_sub_f32_e32 v242, v242, v104
	v_sub_f32_e32 v245, v245, v104
	v_sub_f32_e32 v244, v244, v104
	v_pk_mul_f32 v[244:245], v[100:101], v[244:245] op_sel_hi:[0,1]
	v_pk_mul_f32 v[242:243], v[100:101], v[242:243] op_sel_hi:[0,1]
	v_pk_fma_f32 v[242:243], v[174:175], v[242:243], v[178:179]
	v_pk_fma_f32 v[244:245], v[172:173], v[244:245], v[176:177]
	v_pk_fma_f32 v[86:87], v[86:87], v[124:125], v[242:243]
	v_pk_fma_f32 v[88:89], v[88:89], v[122:123], v[244:245]
	global_store_dwordx4 v[110:111], v[86:89], off offset:512
	s_nop 0
	s_waitcnt vmcnt(3)
	v_sub_f32_e32 v247, v247, v104
	v_sub_f32_e32 v246, v246, v104
	v_sub_f32_e32 v249, v249, v104
	v_sub_f32_e32 v248, v248, v104
	v_pk_mul_f32 v[248:249], v[100:101], v[248:249] op_sel_hi:[0,1]
	v_pk_mul_f32 v[246:247], v[100:101], v[246:247] op_sel_hi:[0,1]
	v_pk_fma_f32 v[246:247], v[166:167], v[246:247], v[168:169]
	v_pk_fma_f32 v[248:249], v[180:181], v[248:249], v[182:183]
	v_pk_fma_f32 v[82:83], v[82:83], v[120:121], v[246:247]
	v_pk_fma_f32 v[84:85], v[84:85], v[118:119], v[248:249]
	global_store_dwordx4 v[110:111], v[82:85], off offset:576
	s_cbranch_vccnz .LBB0_649
	s_nop 0
	v_mov_b32_e32 v98, v228
	v_mov_b32_e32 v99, v229
	v_mov_b32_e32 v102, v99
.LBB0_649:
	s_and_b64 vcc, exec, s[38:39]
	s_cbranch_vccnz .Lst_4
	v_lshl_add_u64 v[226:227], v[186:187], 3, s[6:7]
	global_load_dwordx2 v[228:229], v[226:227], off offset:1024
.Lst_4:
	s_nop 0
	v_or_b32_e32 v82, 48, v188
	v_ashrrev_i32_e32 v83, 31, v82
	v_lshlrev_b64 v[82:83], 10, v[82:83]
	v_lshl_add_u64 v[82:83], v[82:83], 0, v[184:185]
	v_lshlrev_b64 v[86:87], 2, v[82:83]
	v_lshl_add_u64 v[88:89], s[62:63], 0, v[86:87]
	global_load_dwordx4 v[234:237], v[88:89], off
	global_load_dwordx4 v[238:241], v[88:89], off offset:64
	global_load_dwordx4 v[242:245], v[88:89], off offset:512
	global_load_dwordx4 v[246:249], v[88:89], off offset:576
	v_lshl_add_u64 v[86:87], s[10:11], 0, v[86:87]
	s_and_b64 vcc, exec, s[38:39]
	s_waitcnt vmcnt(3)
	v_sub_f32_e32 v235, v235, v98
	v_sub_f32_e32 v234, v234, v98
	v_sub_f32_e32 v237, v237, v98
	v_sub_f32_e32 v236, v236, v98
	v_pk_mul_f32 v[236:237], v[102:103], v[236:237] op_sel_hi:[0,1]
	v_pk_mul_f32 v[234:235], v[102:103], v[234:235] op_sel_hi:[0,1]
	v_pk_fma_f32 v[234:235], v[158:159], v[234:235], v[162:163]
	v_pk_fma_f32 v[236:237], v[156:157], v[236:237], v[160:161]
	v_pk_fma_f32 v[78:79], v[78:79], v[130:131], v[234:235]
	v_pk_fma_f32 v[80:81], v[80:81], v[132:133], v[236:237]
	global_store_dwordx4 v[86:87], v[78:81], off
	s_nop 0
	s_waitcnt vmcnt(3)
	v_sub_f32_e32 v239, v239, v98
	v_sub_f32_e32 v238, v238, v98
	v_sub_f32_e32 v241, v241, v98
	v_sub_f32_e32 v240, v240, v98
	v_pk_mul_f32 v[240:241], v[102:103], v[240:241] op_sel_hi:[0,1]
	v_pk_mul_f32 v[238:239], v[102:103], v[238:239] op_sel_hi:[0,1]
	v_pk_fma_f32 v[238:239], v[152:153], v[238:239], v[154:155]
	v_pk_fma_f32 v[240:241], v[164:165], v[240:241], v[170:171]
	v_pk_fma_f32 v[74:75], v[74:75], v[128:129], v[238:239]
	v_pk_fma_f32 v[76:77], v[76:77], v[126:127], v[240:241]
	global_store_dwordx4 v[86:87], v[74:77], off offset:64
	s_nop 0
	s_waitcnt vmcnt(3)
	v_sub_f32_e32 v243, v243, v98
	v_sub_f32_e32 v242, v242, v98
	v_sub_f32_e32 v245, v245, v98
	v_sub_f32_e32 v244, v244, v98
	v_pk_mul_f32 v[244:245], v[102:103], v[244:245] op_sel_hi:[0,1]
	v_pk_mul_f32 v[242:243], v[102:103], v[242:243] op_sel_hi:[0,1]
	v_pk_fma_f32 v[242:243], v[174:175], v[242:243], v[178:179]
	v_pk_fma_f32 v[244:245], v[172:173], v[244:245], v[176:177]
	v_pk_fma_f32 v[70:71], v[70:71], v[124:125], v[242:243]
	v_pk_fma_f32 v[72:73], v[72:73], v[122:123], v[244:245]
	global_store_dwordx4 v[86:87], v[70:73], off offset:512
	s_nop 0
	s_waitcnt vmcnt(3)
	v_sub_f32_e32 v249, v249, v98
	v_sub_f32_e32 v247, v247, v98
	v_sub_f32_e32 v246, v246, v98
	v_sub_f32_e32 v248, v248, v98
	v_pk_mul_f32 v[248:249], v[102:103], v[248:249] op_sel_hi:[0,1]
	v_pk_mul_f32 v[246:247], v[102:103], v[246:247] op_sel_hi:[0,1]
	v_pk_fma_f32 v[246:247], v[166:167], v[246:247], v[168:169]
	v_pk_fma_f32 v[248:249], v[180:181], v[248:249], v[182:183]
	v_pk_fma_f32 v[66:67], v[66:67], v[120:121], v[246:247]
	v_pk_fma_f32 v[68:69], v[68:69], v[118:119], v[248:249]
	global_store_dwordx4 v[86:87], v[66:69], off offset:576
	v_mov_b32_e32 v70, 1.0
	v_mov_b32_e32 v74, 0
	v_mov_b32_e32 v66, 0
	v_mov_b32_e32 v72, 1.0
	s_cbranch_vccnz .LBB0_651
	v_mov_b32_e32 v74, v228
	v_mov_b32_e32 v75, v229
	v_mov_b32_e32 v72, v75
.LBB0_651:
	s_and_b64 vcc, exec, s[38:39]
	s_cbranch_vccnz .Lst_5
	v_lshl_add_u64 v[226:227], v[186:187], 3, s[6:7]
	global_load_dwordx2 v[228:229], v[226:227], off offset:1152
.Lst_5:
	v_lshlrev_b64 v[68:69], 10, v[188:189]
	v_lshl_add_u64 v[68:69], v[68:69], 0, v[184:185]
	v_lshl_add_u64 v[80:81], v[68:69], 2, v[200:201]
	v_lshl_add_u64 v[82:83], s[62:63], 0, v[80:81]
	global_load_dwordx4 v[234:237], v[82:83], off
	global_load_dwordx4 v[238:241], v[82:83], off offset:64
	global_load_dwordx4 v[242:245], v[82:83], off offset:512
	global_load_dwordx4 v[246:249], v[82:83], off offset:576
	v_lshl_add_u64 v[80:81], s[10:11], 0, v[80:81]
	s_and_b64 vcc, exec, s[38:39]
	s_waitcnt vmcnt(3)
	v_sub_f32_e32 v235, v235, v74
	v_sub_f32_e32 v234, v234, v74
	v_sub_f32_e32 v237, v237, v74
	v_sub_f32_e32 v236, v236, v74
	v_pk_mul_f32 v[236:237], v[72:73], v[236:237] op_sel_hi:[0,1]
	v_pk_mul_f32 v[234:235], v[72:73], v[234:235] op_sel_hi:[0,1]
	v_pk_fma_f32 v[234:235], v[158:159], v[234:235], v[162:163]
	v_pk_fma_f32 v[236:237], v[156:157], v[236:237], v[160:161]
	v_pk_fma_f32 v[62:63], v[62:63], v[130:131], v[234:235]
	v_pk_fma_f32 v[64:65], v[64:65], v[132:133], v[236:237]
	global_store_dwordx4 v[80:81], v[62:65], off
	s_nop 0
	s_waitcnt vmcnt(3)
	v_sub_f32_e32 v239, v239, v74
	v_sub_f32_e32 v238, v238, v74
	v_sub_f32_e32 v241, v241, v74
	v_sub_f32_e32 v240, v240, v74
	v_pk_mul_f32 v[240:241], v[72:73], v[240:241] op_sel_hi:[0,1]
	v_pk_mul_f32 v[238:239], v[72:73], v[238:239] op_sel_hi:[0,1]
	v_pk_fma_f32 v[238:239], v[152:153], v[238:239], v[154:155]
	v_pk_fma_f32 v[240:241], v[164:165], v[240:241], v[170:171]
	v_pk_fma_f32 v[58:59], v[58:59], v[128:129], v[238:239]
	v_pk_fma_f32 v[60:61], v[60:61], v[126:127], v[240:241]
	global_store_dwordx4 v[80:81], v[58:61], off offset:64
	s_nop 0
	s_waitcnt vmcnt(3)
	v_sub_f32_e32 v243, v243, v74
	v_sub_f32_e32 v242, v242, v74
	v_sub_f32_e32 v245, v245, v74
	v_sub_f32_e32 v244, v244, v74
	v_pk_mul_f32 v[244:245], v[72:73], v[244:245] op_sel_hi:[0,1]
	v_pk_mul_f32 v[242:243], v[72:73], v[242:243] op_sel_hi:[0,1]
	v_pk_fma_f32 v[242:243], v[174:175], v[242:243], v[178:179]
	v_pk_fma_f32 v[244:245], v[172:173], v[244:245], v[176:177]
	v_pk_fma_f32 v[54:55], v[54:55], v[124:125], v[242:243]
	v_pk_fma_f32 v[56:57], v[56:57], v[122:123], v[244:245]
	global_store_dwordx4 v[80:81], v[54:57], off offset:512
	s_nop 0
	s_waitcnt vmcnt(3)
	v_sub_f32_e32 v247, v247, v74
	v_sub_f32_e32 v246, v246, v74
	v_sub_f32_e32 v249, v249, v74
	v_sub_f32_e32 v248, v248, v74
	v_pk_mul_f32 v[248:249], v[72:73], v[248:249] op_sel_hi:[0,1]
	v_pk_mul_f32 v[246:247], v[72:73], v[246:247] op_sel_hi:[0,1]
	v_pk_fma_f32 v[246:247], v[166:167], v[246:247], v[168:169]
	v_pk_fma_f32 v[248:249], v[180:181], v[248:249], v[182:183]
	v_pk_fma_f32 v[50:51], v[50:51], v[120:121], v[246:247]
	v_pk_fma_f32 v[52:53], v[52:53], v[118:119], v[248:249]
	global_store_dwordx4 v[80:81], v[50:53], off offset:576
	s_cbranch_vccnz .LBB0_653
	s_nop 0
	v_mov_b32_e32 v66, v228
	v_mov_b32_e32 v67, v229
	v_mov_b32_e32 v70, v67
.LBB0_653:
	s_and_b64 vcc, exec, s[38:39]
	s_cbranch_vccnz .Lst_6
	v_lshl_add_u64 v[226:227], v[186:187], 3, s[6:7]
	global_load_dwordx2 v[228:229], v[226:227], off offset:1280
.Lst_6:
	v_lshl_add_u64 v[54:55], v[68:69], 2, v[202:203]
	v_lshl_add_u64 v[56:57], s[62:63], 0, v[54:55]
	global_load_dwordx4 v[234:237], v[56:57], off
	global_load_dwordx4 v[238:241], v[56:57], off offset:64
	global_load_dwordx4 v[242:245], v[56:57], off offset:512
	global_load_dwordx4 v[246:249], v[56:57], off offset:576
	v_lshl_add_u64 v[54:55], s[10:11], 0, v[54:55]
	s_and_b64 vcc, exec, s[38:39]
	s_waitcnt vmcnt(3)
	v_sub_f32_e32 v235, v235, v66
	v_sub_f32_e32 v234, v234, v66
	v_sub_f32_e32 v237, v237, v66
	v_sub_f32_e32 v236, v236, v66
	v_pk_mul_f32 v[236:237], v[70:71], v[236:237] op_sel_hi:[0,1]
	v_pk_mul_f32 v[234:235], v[70:71], v[234:235] op_sel_hi:[0,1]
	v_pk_fma_f32 v[234:235], v[158:159], v[234:235], v[162:163]
	v_pk_fma_f32 v[236:237], v[156:157], v[236:237], v[160:161]
	v_pk_fma_f32 v[46:47], v[46:47], v[130:131], v[234:235]
	v_pk_fma_f32 v[48:49], v[48:49], v[132:133], v[236:237]
	global_store_dwordx4 v[54:55], v[46:49], off
	s_nop 0
	s_waitcnt vmcnt(3)
	v_sub_f32_e32 v239, v239, v66
	v_sub_f32_e32 v238, v238, v66
	v_sub_f32_e32 v241, v241, v66
	v_sub_f32_e32 v240, v240, v66
	v_pk_mul_f32 v[240:241], v[70:71], v[240:241] op_sel_hi:[0,1]
	v_pk_mul_f32 v[238:239], v[70:71], v[238:239] op_sel_hi:[0,1]
	v_pk_fma_f32 v[238:239], v[152:153], v[238:239], v[154:155]
	v_pk_fma_f32 v[240:241], v[164:165], v[240:241], v[170:171]
	v_pk_fma_f32 v[42:43], v[42:43], v[128:129], v[238:239]
	v_pk_fma_f32 v[44:45], v[44:45], v[126:127], v[240:241]
	global_store_dwordx4 v[54:55], v[42:45], off offset:64
	s_nop 0
	s_waitcnt vmcnt(3)
	v_sub_f32_e32 v243, v243, v66
	v_sub_f32_e32 v242, v242, v66
	v_sub_f32_e32 v245, v245, v66
	v_sub_f32_e32 v244, v244, v66
	v_pk_mul_f32 v[244:245], v[70:71], v[244:245] op_sel_hi:[0,1]
	v_pk_mul_f32 v[242:243], v[70:71], v[242:243] op_sel_hi:[0,1]
	v_pk_fma_f32 v[242:243], v[174:175], v[242:243], v[178:179]
	v_pk_fma_f32 v[244:245], v[172:173], v[244:245], v[176:177]
	v_pk_fma_f32 v[38:39], v[38:39], v[124:125], v[242:243]
	v_pk_fma_f32 v[40:41], v[40:41], v[122:123], v[244:245]
	global_store_dwordx4 v[54:55], v[38:41], off offset:512
	s_nop 0
	s_waitcnt vmcnt(3)
	v_sub_f32_e32 v249, v249, v66
	v_sub_f32_e32 v247, v247, v66
	v_sub_f32_e32 v246, v246, v66
	v_sub_f32_e32 v248, v248, v66
	v_pk_mul_f32 v[248:249], v[70:71], v[248:249] op_sel_hi:[0,1]
	v_pk_mul_f32 v[246:247], v[70:71], v[246:247] op_sel_hi:[0,1]
	v_pk_fma_f32 v[246:247], v[166:167], v[246:247], v[168:169]
	v_pk_fma_f32 v[248:249], v[180:181], v[248:249], v[182:183]
	v_pk_fma_f32 v[34:35], v[34:35], v[120:121], v[246:247]
	v_pk_fma_f32 v[36:37], v[36:37], v[118:119], v[248:249]
	global_store_dwordx4 v[54:55], v[34:37], off offset:576
	v_mov_b32_e32 v38, 1.0
	v_mov_b32_e32 v42, 0
	v_mov_b32_e32 v34, 0
	v_mov_b32_e32 v40, 1.0
	s_cbranch_vccnz .LBB0_655
	v_mov_b32_e32 v42, v228
	v_mov_b32_e32 v43, v229
	v_mov_b32_e32 v40, v43
.LBB0_655:
	s_and_b64 vcc, exec, s[38:39]
	s_cbranch_vccnz .Lst_7
	v_lshl_add_u64 v[226:227], v[186:187], 3, s[6:7]
	global_load_dwordx2 v[228:229], v[226:227], off offset:1408
.Lst_7:
	v_lshlrev_b64 v[36:37], 10, v[188:189]
	v_lshl_add_u64 v[36:37], v[36:37], 0, v[184:185]
	v_lshl_add_u64 v[48:49], v[36:37], 2, v[204:205]
	v_lshl_add_u64 v[50:51], s[62:63], 0, v[48:49]
	global_load_dwordx4 v[234:237], v[50:51], off
	global_load_dwordx4 v[238:241], v[50:51], off offset:64
	global_load_dwordx4 v[242:245], v[50:51], off offset:512
	global_load_dwordx4 v[246:249], v[50:51], off offset:576
	v_lshl_add_u64 v[48:49], s[10:11], 0, v[48:49]
	s_and_b64 vcc, exec, s[38:39]
	s_waitcnt vmcnt(3)
	v_sub_f32_e32 v235, v235, v42
	v_sub_f32_e32 v234, v234, v42
	v_sub_f32_e32 v237, v237, v42
	v_sub_f32_e32 v236, v236, v42
	v_pk_mul_f32 v[236:237], v[40:41], v[236:237] op_sel_hi:[0,1]
	v_pk_mul_f32 v[234:235], v[40:41], v[234:235] op_sel_hi:[0,1]
	v_pk_fma_f32 v[234:235], v[158:159], v[234:235], v[162:163]
	v_pk_fma_f32 v[236:237], v[156:157], v[236:237], v[160:161]
	v_pk_fma_f32 v[30:31], v[30:31], v[130:131], v[234:235]
	v_pk_fma_f32 v[32:33], v[32:33], v[132:133], v[236:237]
	global_store_dwordx4 v[48:49], v[30:33], off
	s_nop 0
	s_waitcnt vmcnt(3)
	v_sub_f32_e32 v239, v239, v42
	v_sub_f32_e32 v238, v238, v42
	v_sub_f32_e32 v241, v241, v42
	v_sub_f32_e32 v240, v240, v42
	v_pk_mul_f32 v[240:241], v[40:41], v[240:241] op_sel_hi:[0,1]
	v_pk_mul_f32 v[238:239], v[40:41], v[238:239] op_sel_hi:[0,1]
	v_pk_fma_f32 v[238:239], v[152:153], v[238:239], v[154:155]
	v_pk_fma_f32 v[240:241], v[164:165], v[240:241], v[170:171]
	v_pk_fma_f32 v[26:27], v[26:27], v[128:129], v[238:239]
	v_pk_fma_f32 v[28:29], v[28:29], v[126:127], v[240:241]
	global_store_dwordx4 v[48:49], v[26:29], off offset:64
	s_nop 0
	s_waitcnt vmcnt(3)
	v_sub_f32_e32 v243, v243, v42
	v_sub_f32_e32 v242, v242, v42
	v_sub_f32_e32 v245, v245, v42
	v_sub_f32_e32 v244, v244, v42
	v_pk_mul_f32 v[244:245], v[40:41], v[244:245] op_sel_hi:[0,1]
	v_pk_mul_f32 v[242:243], v[40:41], v[242:243] op_sel_hi:[0,1]
	v_pk_fma_f32 v[242:243], v[174:175], v[242:243], v[178:179]
	v_pk_fma_f32 v[244:245], v[172:173], v[244:245], v[176:177]
	v_pk_fma_f32 v[22:23], v[22:23], v[124:125], v[242:243]
	v_pk_fma_f32 v[24:25], v[24:25], v[122:123], v[244:245]
	global_store_dwordx4 v[48:49], v[22:25], off offset:512
	s_nop 0
	s_waitcnt vmcnt(3)
	v_sub_f32_e32 v247, v247, v42
	v_sub_f32_e32 v246, v246, v42
	v_sub_f32_e32 v249, v249, v42
	v_sub_f32_e32 v248, v248, v42
	v_pk_mul_f32 v[248:249], v[40:41], v[248:249] op_sel_hi:[0,1]
	v_pk_mul_f32 v[246:247], v[40:41], v[246:247] op_sel_hi:[0,1]
	v_pk_fma_f32 v[246:247], v[166:167], v[246:247], v[168:169]
	v_pk_fma_f32 v[248:249], v[180:181], v[248:249], v[182:183]
	v_pk_fma_f32 v[18:19], v[18:19], v[120:121], v[246:247]
	v_pk_fma_f32 v[20:21], v[20:21], v[118:119], v[248:249]
	global_store_dwordx4 v[48:49], v[18:21], off offset:576
	s_cbranch_vccnz .LBB0_657
	s_nop 0
	v_mov_b32_e32 v34, v228
	v_mov_b32_e32 v35, v229
	v_mov_b32_e32 v38, v35
